# conv unit prologue: U-staging loads de-serialized (halo ushort loads into dedicated regs, single vmcnt(0) after all 9/10 iterations)
# speedup vs baseline: 1.0074x; 1.0074x over previous
; template <int NQ, int NB, int L>
; __device__ __forceinline__ void conv_unit(LAS unsigned char* lds, const Args& a, int j, int seq0, int c, int tid) {
;     ...
;     {
;         const u32x4* src = (const u32x4*)(FK + (size_t)c * LEN);
; #pragma unroll
;         for (int it = 0; it < NF; ++it) { const int i = it * 512 + tid; fkr[it] = src[i < LEN / 8 ? i : 0]; }
;     }
;     {
;         const float w0 = cw[2048 + c], w1 = cw[3072 + 2048 + c], w2 = cw[2 * 3072 + 2048 + c], bb = cb[2048 + c];
;         constexpr int NCH = LPD / 8, NIT = (NB * NCH + 511) / 512;
;         u32x4 raws[NIT]; unsigned halos[NIT];
; #pragma unroll
;         for (int it = 0; it < NIT; ++it) {
;             const int idx = it * 512 + tid; const int b = idx / NCH, ch = idx % NCH, p = ch * 8 - PADL;
;             raws[it] = (u32x4){0u, 0u, 0u, 0u}; halos[it] = 0u;
;             if (idx < NB * NCH && p >= 0 && p < L) {
;                 const bf16_t* row = V + seq_off_ch(seq0 + b) + (size_t)c * LS + XPAD + p;
;                 raws[it] = *(const u32x4*)row;
;                 const unsigned xm = p > 0 ? (unsigned)row[-1] : 0u, xp = (p + 8 < L) ? (unsigned)row[8] : 0u;
;                 halos[it] = xm | (xp << 16);
;             }
;         }
.LBB0_1178:
	v_mov_b32_e32 v190, v215
	s_movk_i32 s4, 0x480
	s_movk_i32 s6, 0x280
	s_movk_i32 s8, 0x80
	s_mov_b64 s[2:3], -1
	s_cmpk_gt_i32 s52, 0x3ff
	v_cmp_gt_i32_e64 s[4:5], s4, v190
	v_add_u32_e32 v191, 0x200, v190
	v_cmp_gt_i32_e64 s[6:7], s6, v190
	v_add_u32_e32 v192, 0x400, v190
	v_cmp_gt_i32_e64 s[8:9], s8, v190
	s_cbranch_scc0 .LBB0_1429
	v_mov_b32_e32 v110, 0
	v_mov_b32_e32 v111, 0
	v_mov_b32_e32 v112, 0
	v_mov_b32_e32 v113, 0
	v_mov_b32_e32 v114, 0
	v_mov_b32_e32 v115, 0
	v_mov_b32_e32 v116, 0
	v_mov_b32_e32 v117, 0
	v_mov_b32_e32 v118, 0
	v_mov_b32_e32 v119, 0
	v_mov_b32_e32 v120, 0
	v_mov_b32_e32 v121, 0
	v_mov_b32_e32 v122, 0
	v_mov_b32_e32 v123, 0
	v_mov_b32_e32 v124, 0
	v_mov_b32_e32 v125, 0
	v_mov_b32_e32 v126, 0
	v_mov_b32_e32 v127, 0
	v_mov_b32_e32 v128, 0
	v_mov_b32_e32 v129, 0
	s_add_i32 s2, s52, 0xfffffc00
	s_lshl_b32 s3, s52, 3
	s_and_b32 s53, s3, 8
	s_lshr_b32 s62, s2, 1
	s_or_b32 s50, s53, 4
	s_mul_i32 s3, s62, 0x4800
	v_readlane_b32 s10, v254, 19
	s_mul_hi_u32 s2, s62, 0x4800
	s_add_u32 s66, s10, s3
	v_readlane_b32 s3, v254, 21
	s_addc_u32 s67, s3, s2
	s_or_b32 s56, s62, 0x800
	s_lshl_b64 s[2:3], s[56:57], 2
	s_mov_b32 s63, s57
	s_add_u32 s10, s87, s2
	v_cndmask_b32_e64 v58, 0, v190, s[4:5]
	v_cndmask_b32_e64 v60, 0, v191, s[6:7]
	s_addc_u32 s11, s88, s3
	s_lshl_b64 s[12:13], s[62:63], 2
	v_ashrrev_i32_e32 v59, 31, v58
	v_ashrrev_i32_e32 v61, 31, v60
	v_cndmask_b32_e64 v62, 0, v192, s[8:9]
	s_add_u32 s12, s87, s12
	v_lshl_add_u64 v[0:1], v[58:59], 4, s[66:67]
	v_lshl_add_u64 v[4:5], v[60:61], 4, s[66:67]
	v_ashrrev_i32_e32 v63, 31, v62
	s_addc_u32 s13, s88, s13
	v_mov_b32_e32 v12, 0x5000
	v_mov_b32_e32 v15, 0
	global_load_dwordx4 v[0:3], v[0:1], off
	s_nop 0
	global_load_dwordx4 v[4:7], v[4:5], off
	v_lshl_add_u64 v[8:9], v[62:63], 4, s[66:67]
	global_load_dword v66, v12, s[12:13]
	v_mov_b32_e32 v12, 0x8000
	s_add_u32 s2, s89, s2
	global_load_dwordx4 v[8:11], v[8:9], off
	s_addc_u32 s3, s90, s3
	global_load_dword v64, v12, s[12:13]
	global_load_dword v68, v15, s[10:11]
	global_load_dword v70, v15, s[2:3]
	s_mul_i32 s3, s62, 0x2080
	s_mul_hi_u32 s2, s62, 0x2080
	s_add_u32 s70, s58, s3
	s_addc_u32 s71, s59, s2
	s_mov_b32 s2, 0xe32943
	v_mul_hi_i32 v12, v190, s2
	v_lshrrev_b32_e32 v16, 31, v12
	v_ashrrev_i32_e32 v17, 1, v12
	v_add_u32_e32 v65, v17, v16
	v_mul_i32_i24_e32 v12, 0x241, v65
	v_sub_u32_e32 v67, v190, v12
	s_movk_i32 s2, 0x1208
	v_cmp_gt_i32_e32 vcc, s2, v190
	v_subrev_u32_e32 v12, 28, v67
	s_movk_i32 s2, 0x202
	v_cmp_gt_u32_e64 s[18:19], s2, v12
	v_readfirstlane_b32 s56, v190
	s_and_b64 s[2:3], vcc, s[18:19]
	v_mov_b32_e32 v14, 0
	v_mov_b32_e32 v13, 0
	v_mov_b32_e32 v12, 0
	v_mov_b32_e32 v84, 0
	s_and_saveexec_b64 s[10:11], s[2:3]
	s_cbranch_execz .LBB0_1189
	v_add3_u32 v14, v17, v16, s50
	v_cmp_lt_i32_e64 s[2:3], 3, v14
	s_and_saveexec_b64 s[12:13], s[2:3]
	s_xor_b64 s[2:3], exec, s[12:13]
	v_add_u32_e32 v12, -4, v14
	s_mov_b32 s12, 0x410000
	v_mov_b64_e32 v[14:15], 0x2040000
	v_mad_u64_u32 v[12:13], s[12:13], v12, s12, v[14:15]
	s_andn2_saveexec_b64 s[2:3], s[2:3]
	s_mov_b32 s12, 0x810000
	v_mad_i64_i32 v[12:13], s[12:13], v14, s12, 0
	s_or_b64 exec, exec, s[2:3]
	v_lshl_add_u64 v[12:13], v[12:13], 1, s[70:71]
	v_lshlrev_b32_e32 v32, 4, v67
	v_lshl_add_u64 v[16:17], v[12:13], 0, v[32:33]
	global_load_dwordx4 v[12:15], v[16:17], off offset:-352
	v_cmp_lt_u32_e64 s[2:3], 28, v67
	v_mov_b32_e32 v19, 0
	v_mov_b32_e32 v18, 0
	s_and_saveexec_b64 s[12:13], s[2:3]
	s_cbranch_execz .LBB0_1186
	global_load_ushort v110, v[16:17], off offset:-354
.LBB0_1186:
	s_or_b64 exec, exec, s[12:13]
	s_movk_i32 s2, 0x21d
	v_cmp_gt_u32_e64 s[2:3], s2, v67
	s_and_saveexec_b64 s[12:13], s[2:3]
	s_cbranch_execz .LBB0_1188
	global_load_ushort v111, v[16:17], off offset:-336

; template <int NQ, int NB, int L>
; __device__ __forceinline__ void conv_unit(LAS unsigned char* lds, const Args& a, int j, int seq0, int c, int tid) {
;     ...
; #pragma unroll
;         for (int it = 0; it < NIT; ++it) {
;             const int idx = it * 512 + tid; const int b = idx / NCH, ch = idx % NCH, p = ch * 8 - PADL;
;             raws[it] = (u32x4){0u, 0u, 0u, 0u}; halos[it] = 0u;
;             if (idx < NB * NCH && p >= 0 && p < L) {
;                 const bf16_t* row = V + seq_off_ch(seq0 + b) + (size_t)c * LS + XPAD + p;
;                 raws[it] = *(const u32x4*)row;
;                 const unsigned xm = p > 0 ? (unsigned)row[-1] : 0u, xp = (p + 8 < L) ? (unsigned)row[8] : 0u;
;                 halos[it] = xm | (xp << 16);
;             }
;         }
.LBB0_1189:
	s_or_b64 exec, exec, s[10:11]
	s_mov_b32 s2, 0xe32943
	v_mul_hi_i32 v16, v191, s2
	v_lshrrev_b32_e32 v20, 31, v16
	v_ashrrev_i32_e32 v21, 1, v16
	v_add_u32_e32 v69, v21, v20
	v_mul_i32_i24_e32 v16, 0x241, v69
	v_sub_u32_e32 v71, v191, v16
	s_movk_i32 s2, 0x1008
	v_subrev_u32_e32 v16, 28, v71
	s_movk_i32 s10, 0x202
	v_cmp_gt_i32_e64 s[2:3], s2, v190
	v_cmp_gt_u32_e64 s[22:23], s10, v16
	s_and_b64 s[10:11], s[2:3], s[22:23]
	v_mov_b32_e32 v19, 0
	v_mov_b32_e32 v18, 0
	v_mov_b32_e32 v17, 0
	v_mov_b32_e32 v16, 0
	v_mov_b32_e32 v87, 0
	s_and_saveexec_b64 s[12:13], s[10:11]
	s_cbranch_execz .LBB0_1199
	v_add3_u32 v18, v21, v20, s50
	v_cmp_lt_i32_e64 s[10:11], 3, v18
	s_and_saveexec_b64 s[14:15], s[10:11]
	s_xor_b64 s[10:11], exec, s[14:15]
	v_add_u32_e32 v16, -4, v18
	s_mov_b32 s14, 0x410000
	v_mov_b64_e32 v[18:19], 0x2040000
	v_mad_u64_u32 v[16:17], s[14:15], v16, s14, v[18:19]
	s_andn2_saveexec_b64 s[10:11], s[10:11]
	s_mov_b32 s14, 0x810000
	v_mad_i64_i32 v[16:17], s[14:15], v18, s14, 0
	s_or_b64 exec, exec, s[10:11]
	v_lshl_add_u64 v[16:17], v[16:17], 1, s[70:71]
	v_lshlrev_b32_e32 v32, 4, v71
	v_lshl_add_u64 v[20:21], v[16:17], 0, v[32:33]
	global_load_dwordx4 v[16:19], v[20:21], off offset:-352
	v_cmp_lt_u32_e64 s[10:11], 28, v71
	v_mov_b32_e32 v23, 0
	v_mov_b32_e32 v22, 0
	s_and_saveexec_b64 s[14:15], s[10:11]
	s_cbranch_execz .LBB0_1196
	global_load_ushort v112, v[20:21], off offset:-354
.LBB0_1196:
	s_or_b64 exec, exec, s[14:15]
	s_movk_i32 s10, 0x21d
	v_cmp_gt_u32_e64 s[10:11], s10, v71
	s_and_saveexec_b64 s[14:15], s[10:11]
	s_cbranch_execz .LBB0_1198
	global_load_ushort v113, v[20:21], off offset:-336

; template <int NQ, int NB, int L>
; __device__ __forceinline__ void conv_unit(LAS unsigned char* lds, const Args& a, int j, int seq0, int c, int tid) {
;     ...
; #pragma unroll
;         for (int it = 0; it < NIT; ++it) {
;             const int idx = it * 512 + tid; const int b = idx / NCH, ch = idx % NCH, p = ch * 8 - PADL;
;             raws[it] = (u32x4){0u, 0u, 0u, 0u}; halos[it] = 0u;
;             if (idx < NB * NCH && p >= 0 && p < L) {
;                 const bf16_t* row = V + seq_off_ch(seq0 + b) + (size_t)c * LS + XPAD + p;
;                 raws[it] = *(const u32x4*)row;
;                 const unsigned xm = p > 0 ? (unsigned)row[-1] : 0u, xp = (p + 8 < L) ? (unsigned)row[8] : 0u;
;                 halos[it] = xm | (xp << 16);
;             }
;         }
.LBB0_1199:
	s_or_b64 exec, exec, s[12:13]
	s_mov_b32 s10, 0xe32943
	v_mul_hi_i32 v20, v192, s10
	v_lshrrev_b32_e32 v24, 31, v20
	v_ashrrev_i32_e32 v25, 1, v20
	v_add_u32_e32 v72, v25, v24
	v_mul_i32_i24_e32 v20, 0x241, v72
	v_sub_u32_e32 v73, v192, v20
	s_movk_i32 s10, 0xe08
	v_subrev_u32_e32 v20, 28, v73
	s_movk_i32 s12, 0x202
	v_cmp_gt_i32_e64 s[10:11], s10, v190
	v_cmp_gt_u32_e64 s[26:27], s12, v20
	s_and_b64 s[12:13], s[10:11], s[26:27]
	v_mov_b32_e32 v23, 0
	v_mov_b32_e32 v22, 0
	v_mov_b32_e32 v21, 0
	v_mov_b32_e32 v20, 0
	v_mov_b32_e32 v90, 0
	s_and_saveexec_b64 s[14:15], s[12:13]
	s_cbranch_execz .LBB0_1209
	v_add3_u32 v22, v25, v24, s50
	v_cmp_lt_i32_e64 s[12:13], 3, v22
	s_and_saveexec_b64 s[16:17], s[12:13]
	s_xor_b64 s[12:13], exec, s[16:17]
	v_add_u32_e32 v20, -4, v22
	s_mov_b32 s16, 0x410000
	v_mov_b64_e32 v[22:23], 0x2040000
	v_mad_u64_u32 v[20:21], s[16:17], v20, s16, v[22:23]
	s_andn2_saveexec_b64 s[12:13], s[12:13]
	s_mov_b32 s16, 0x810000
	v_mad_i64_i32 v[20:21], s[16:17], v22, s16, 0
	s_or_b64 exec, exec, s[12:13]
	v_lshl_add_u64 v[20:21], v[20:21], 1, s[70:71]
	v_lshlrev_b32_e32 v32, 4, v73
	v_lshl_add_u64 v[24:25], v[20:21], 0, v[32:33]
	global_load_dwordx4 v[20:23], v[24:25], off offset:-352
	v_cmp_lt_u32_e64 s[12:13], 28, v73
	v_mov_b32_e32 v27, 0
	v_mov_b32_e32 v26, 0
	s_and_saveexec_b64 s[16:17], s[12:13]
	s_cbranch_execz .LBB0_1206
	global_load_ushort v114, v[24:25], off offset:-354
.LBB0_1206:
	s_or_b64 exec, exec, s[16:17]
	s_movk_i32 s12, 0x21d
	v_cmp_gt_u32_e64 s[12:13], s12, v73
	s_and_saveexec_b64 s[16:17], s[12:13]
	s_cbranch_execz .LBB0_1208
	global_load_ushort v115, v[24:25], off offset:-336

; template <int NQ, int NB, int L>
; __device__ __forceinline__ void conv_unit(LAS unsigned char* lds, const Args& a, int j, int seq0, int c, int tid) {
;     ...
; #pragma unroll
;         for (int it = 0; it < NIT; ++it) {
;             const int idx = it * 512 + tid; const int b = idx / NCH, ch = idx % NCH, p = ch * 8 - PADL;
;             raws[it] = (u32x4){0u, 0u, 0u, 0u}; halos[it] = 0u;
;             if (idx < NB * NCH && p >= 0 && p < L) {
;                 const bf16_t* row = V + seq_off_ch(seq0 + b) + (size_t)c * LS + XPAD + p;
;                 raws[it] = *(const u32x4*)row;
;                 const unsigned xm = p > 0 ? (unsigned)row[-1] : 0u, xp = (p + 8 < L) ? (unsigned)row[8] : 0u;
;                 halos[it] = xm | (xp << 16);
;             }
;         }
.LBB0_1209:
	s_or_b64 exec, exec, s[14:15]
	v_add_u32_e32 v24, 0x600, v190
	s_mov_b32 s12, 0xe32943
	v_mul_hi_i32 v25, v24, s12
	v_lshrrev_b32_e32 v28, 31, v25
	v_ashrrev_i32_e32 v29, 1, v25
	v_add_u32_e32 v74, v29, v28
	v_mul_i32_i24_e32 v25, 0x241, v74
	v_sub_u32_e32 v75, v24, v25
	s_movk_i32 s12, 0xc08
	v_subrev_u32_e32 v24, 28, v75
	s_movk_i32 s14, 0x202
	v_cmp_gt_i32_e64 s[12:13], s12, v190
	v_cmp_gt_u32_e64 s[30:31], s14, v24
	s_and_b64 s[14:15], s[12:13], s[30:31]
	v_mov_b32_e32 v27, 0
	v_mov_b32_e32 v26, 0
	v_mov_b32_e32 v25, 0
	v_mov_b32_e32 v24, 0
	v_mov_b32_e32 v91, 0
	s_and_saveexec_b64 s[16:17], s[14:15]
	s_cbranch_execz .LBB0_1219
	v_add3_u32 v26, v29, v28, s50
	v_cmp_lt_i32_e64 s[14:15], 3, v26
	s_and_saveexec_b64 s[20:21], s[14:15]
	s_xor_b64 s[14:15], exec, s[20:21]
	v_add_u32_e32 v24, -4, v26
	s_mov_b32 s20, 0x410000
	v_mov_b64_e32 v[26:27], 0x2040000
	v_mad_u64_u32 v[24:25], s[20:21], v24, s20, v[26:27]
	s_andn2_saveexec_b64 s[14:15], s[14:15]
	s_mov_b32 s20, 0x810000
	v_mad_i64_i32 v[24:25], s[20:21], v26, s20, 0
	s_or_b64 exec, exec, s[14:15]
	v_lshl_add_u64 v[24:25], v[24:25], 1, s[70:71]
	v_lshlrev_b32_e32 v32, 4, v75
	v_lshl_add_u64 v[28:29], v[24:25], 0, v[32:33]
	global_load_dwordx4 v[24:27], v[28:29], off offset:-352
	v_cmp_lt_u32_e64 s[14:15], 28, v75
	v_mov_b32_e32 v31, 0
	v_mov_b32_e32 v30, 0
	s_and_saveexec_b64 s[20:21], s[14:15]
	s_cbranch_execz .LBB0_1216
	global_load_ushort v116, v[28:29], off offset:-354
.LBB0_1216:
	s_or_b64 exec, exec, s[20:21]
	s_movk_i32 s14, 0x21d
	v_cmp_gt_u32_e64 s[14:15], s14, v75
	s_and_saveexec_b64 s[20:21], s[14:15]
	s_cbranch_execz .LBB0_1218
	global_load_ushort v117, v[28:29], off offset:-336

; template <int NQ, int NB, int L>
; __device__ __forceinline__ void conv_unit(LAS unsigned char* lds, const Args& a, int j, int seq0, int c, int tid) {
;     ...
; #pragma unroll
;         for (int it = 0; it < NIT; ++it) {
;             const int idx = it * 512 + tid; const int b = idx / NCH, ch = idx % NCH, p = ch * 8 - PADL;
;             raws[it] = (u32x4){0u, 0u, 0u, 0u}; halos[it] = 0u;
;             if (idx < NB * NCH && p >= 0 && p < L) {
;                 const bf16_t* row = V + seq_off_ch(seq0 + b) + (size_t)c * LS + XPAD + p;
;                 raws[it] = *(const u32x4*)row;
;                 const unsigned xm = p > 0 ? (unsigned)row[-1] : 0u, xp = (p + 8 < L) ? (unsigned)row[8] : 0u;
;                 halos[it] = xm | (xp << 16);
;             }
;         }
.LBB0_1219:
	s_or_b64 exec, exec, s[16:17]
	v_add_u32_e32 v28, 0x800, v190
	s_mov_b32 s14, 0xe32943
	v_mul_hi_i32 v29, v28, s14
	v_lshrrev_b32_e32 v32, 31, v29
	v_ashrrev_i32_e32 v34, 1, v29
	v_add_u32_e32 v76, v34, v32
	v_mul_i32_i24_e32 v29, 0x241, v76
	v_sub_u32_e32 v77, v28, v29
	s_movk_i32 s14, 0xa08
	v_subrev_u32_e32 v28, 28, v77
	s_movk_i32 s16, 0x202
	v_cmp_gt_i32_e64 s[14:15], s14, v190
	v_cmp_gt_u32_e64 s[36:37], s16, v28
	s_and_b64 s[16:17], s[14:15], s[36:37]
	v_mov_b32_e32 v31, 0
	v_mov_b32_e32 v30, 0
	v_mov_b32_e32 v29, 0
	v_mov_b32_e32 v28, 0
	v_mov_b32_e32 v92, 0
	s_and_saveexec_b64 s[20:21], s[16:17]
	s_cbranch_execz .LBB0_1229
	v_add3_u32 v30, v34, v32, s50
	v_cmp_lt_i32_e64 s[16:17], 3, v30
	s_and_saveexec_b64 s[24:25], s[16:17]
	s_xor_b64 s[16:17], exec, s[24:25]
	v_add_u32_e32 v28, -4, v30
	s_mov_b32 s24, 0x410000
	v_mov_b64_e32 v[30:31], 0x2040000
	v_mad_u64_u32 v[28:29], s[24:25], v28, s24, v[30:31]
	s_andn2_saveexec_b64 s[16:17], s[16:17]
	s_mov_b32 s24, 0x810000
	v_mad_i64_i32 v[28:29], s[24:25], v30, s24, 0
	s_or_b64 exec, exec, s[16:17]
	v_lshl_add_u64 v[28:29], v[28:29], 1, s[70:71]
	v_lshlrev_b32_e32 v32, 4, v77
	v_lshl_add_u64 v[34:35], v[28:29], 0, v[32:33]
	global_load_dwordx4 v[28:31], v[34:35], off offset:-352
	v_cmp_lt_u32_e64 s[16:17], 28, v77
	v_mov_b32_e32 v36, 0
	v_mov_b32_e32 v32, 0
	s_and_saveexec_b64 s[24:25], s[16:17]
	s_cbranch_execz .LBB0_1226
	global_load_ushort v118, v[34:35], off offset:-354
.LBB0_1226:
	s_or_b64 exec, exec, s[24:25]
	s_movk_i32 s16, 0x21d
	v_cmp_gt_u32_e64 s[16:17], s16, v77
	s_and_saveexec_b64 s[24:25], s[16:17]
	s_cbranch_execz .LBB0_1228
	global_load_ushort v119, v[34:35], off offset:-336

; template <int NQ, int NB, int L>
; __device__ __forceinline__ void conv_unit(LAS unsigned char* lds, const Args& a, int j, int seq0, int c, int tid) {
;     ...
; #pragma unroll
;         for (int it = 0; it < NIT; ++it) {
;             const int idx = it * 512 + tid; const int b = idx / NCH, ch = idx % NCH, p = ch * 8 - PADL;
;             raws[it] = (u32x4){0u, 0u, 0u, 0u}; halos[it] = 0u;
;             if (idx < NB * NCH && p >= 0 && p < L) {
;                 const bf16_t* row = V + seq_off_ch(seq0 + b) + (size_t)c * LS + XPAD + p;
;                 raws[it] = *(const u32x4*)row;
;                 const unsigned xm = p > 0 ? (unsigned)row[-1] : 0u, xp = (p + 8 < L) ? (unsigned)row[8] : 0u;
;                 halos[it] = xm | (xp << 16);
;             }
;         }
.LBB0_1229:
	s_or_b64 exec, exec, s[20:21]
	v_add_u32_e32 v34, 0xa00, v190
	s_mov_b32 s16, 0xe32943
	v_mul_hi_i32 v35, v34, s16
	v_lshrrev_b32_e32 v32, 31, v35
	v_ashrrev_i32_e32 v38, 1, v35
	v_add_u32_e32 v78, v38, v32
	v_mul_i32_i24_e32 v35, 0x241, v78
	v_sub_u32_e32 v79, v34, v35
	s_movk_i32 s16, 0x808
	v_subrev_u32_e32 v34, 28, v79
	s_movk_i32 s20, 0x202
	v_cmp_gt_i32_e64 s[16:17], s16, v190
	v_cmp_gt_u32_e64 s[38:39], s20, v34
	s_and_b64 s[20:21], s[16:17], s[38:39]
	v_mov_b32_e32 v37, 0
	v_mov_b32_e32 v36, 0
	v_mov_b32_e32 v35, 0
	v_mov_b32_e32 v34, 0
	v_mov_b32_e32 v93, 0
	s_and_saveexec_b64 s[24:25], s[20:21]
	s_cbranch_execz .LBB0_1239
	v_add3_u32 v32, v38, v32, s50
	v_cmp_lt_i32_e64 s[20:21], 3, v32
	s_and_saveexec_b64 s[28:29], s[20:21]
	s_xor_b64 s[20:21], exec, s[28:29]
	v_add_u32_e32 v32, -4, v32
	s_mov_b32 s28, 0x410000
	v_mov_b64_e32 v[34:35], 0x2040000
	v_mad_u64_u32 v[34:35], s[28:29], v32, s28, v[34:35]
	s_andn2_saveexec_b64 s[20:21], s[20:21]
	s_mov_b32 s28, 0x810000
	v_mad_i64_i32 v[34:35], s[28:29], v32, s28, 0
	s_or_b64 exec, exec, s[20:21]
	v_lshl_add_u64 v[34:35], v[34:35], 1, s[70:71]
	v_lshlrev_b32_e32 v32, 4, v79
	v_lshl_add_u64 v[38:39], v[34:35], 0, v[32:33]
	global_load_dwordx4 v[34:37], v[38:39], off offset:-352
	v_cmp_lt_u32_e64 s[20:21], 28, v79
	v_mov_b32_e32 v40, 0
	v_mov_b32_e32 v32, 0
	s_and_saveexec_b64 s[28:29], s[20:21]
	s_cbranch_execz .LBB0_1236
	global_load_ushort v120, v[38:39], off offset:-354
.LBB0_1236:
	s_or_b64 exec, exec, s[28:29]
	s_movk_i32 s20, 0x21d
	v_cmp_gt_u32_e64 s[20:21], s20, v79
	s_and_saveexec_b64 s[28:29], s[20:21]
	s_cbranch_execz .LBB0_1238
	global_load_ushort v121, v[38:39], off offset:-336

; template <int NQ, int NB, int L>
; __device__ __forceinline__ void conv_unit(LAS unsigned char* lds, const Args& a, int j, int seq0, int c, int tid) {
;     ...
; #pragma unroll
;         for (int it = 0; it < NIT; ++it) {
;             const int idx = it * 512 + tid; const int b = idx / NCH, ch = idx % NCH, p = ch * 8 - PADL;
;             raws[it] = (u32x4){0u, 0u, 0u, 0u}; halos[it] = 0u;
;             if (idx < NB * NCH && p >= 0 && p < L) {
;                 const bf16_t* row = V + seq_off_ch(seq0 + b) + (size_t)c * LS + XPAD + p;
;                 raws[it] = *(const u32x4*)row;
;                 const unsigned xm = p > 0 ? (unsigned)row[-1] : 0u, xp = (p + 8 < L) ? (unsigned)row[8] : 0u;
;                 halos[it] = xm | (xp << 16);
;             }
;         }
.LBB0_1239:
	s_or_b64 exec, exec, s[24:25]
	v_add_u32_e32 v38, 0xc00, v190
	s_mov_b32 s20, 0xe32943
	v_mul_hi_i32 v39, v38, s20
	v_lshrrev_b32_e32 v32, 31, v39
	v_ashrrev_i32_e32 v42, 1, v39
	v_add_u32_e32 v80, v42, v32
	v_mul_i32_i24_e32 v39, 0x241, v80
	v_sub_u32_e32 v81, v38, v39
	s_movk_i32 s20, 0x608
	v_subrev_u32_e32 v38, 28, v81
	s_movk_i32 s24, 0x202
	v_cmp_gt_i32_e64 s[20:21], s20, v190
	v_cmp_gt_u32_e64 s[40:41], s24, v38
	s_and_b64 s[24:25], s[20:21], s[40:41]
	v_mov_b32_e32 v41, 0
	v_mov_b32_e32 v40, 0
	v_mov_b32_e32 v39, 0
	v_mov_b32_e32 v38, 0
	v_mov_b32_e32 v94, 0
	s_and_saveexec_b64 s[28:29], s[24:25]
	s_cbranch_execz .LBB0_1249
	v_add3_u32 v32, v42, v32, s50
	v_cmp_lt_i32_e64 s[24:25], 3, v32
	s_and_saveexec_b64 s[34:35], s[24:25]
	s_xor_b64 s[24:25], exec, s[34:35]
	v_add_u32_e32 v32, -4, v32
	s_mov_b32 s34, 0x410000
	v_mov_b64_e32 v[38:39], 0x2040000
	v_mad_u64_u32 v[38:39], s[34:35], v32, s34, v[38:39]
	s_andn2_saveexec_b64 s[24:25], s[24:25]
	s_mov_b32 s34, 0x810000
	v_mad_i64_i32 v[38:39], s[34:35], v32, s34, 0
	s_or_b64 exec, exec, s[24:25]
	v_lshl_add_u64 v[38:39], v[38:39], 1, s[70:71]
	v_lshlrev_b32_e32 v32, 4, v81
	v_lshl_add_u64 v[42:43], v[38:39], 0, v[32:33]
	global_load_dwordx4 v[38:41], v[42:43], off offset:-352
	v_cmp_lt_u32_e64 s[24:25], 28, v81
	v_mov_b32_e32 v44, 0
	v_mov_b32_e32 v32, 0
	s_and_saveexec_b64 s[34:35], s[24:25]
	s_cbranch_execz .LBB0_1246
	global_load_ushort v122, v[42:43], off offset:-354
.LBB0_1246:
	s_or_b64 exec, exec, s[34:35]
	s_movk_i32 s24, 0x21d
	v_cmp_gt_u32_e64 s[24:25], s24, v81
	s_and_saveexec_b64 s[34:35], s[24:25]
	s_cbranch_execz .LBB0_1248
	global_load_ushort v123, v[42:43], off offset:-336

; template <int NQ, int NB, int L>
; __device__ __forceinline__ void conv_unit(LAS unsigned char* lds, const Args& a, int j, int seq0, int c, int tid) {
;     ...
; #pragma unroll
;         for (int it = 0; it < NIT; ++it) {
;             const int idx = it * 512 + tid; const int b = idx / NCH, ch = idx % NCH, p = ch * 8 - PADL;
;             raws[it] = (u32x4){0u, 0u, 0u, 0u}; halos[it] = 0u;
;             if (idx < NB * NCH && p >= 0 && p < L) {
;                 const bf16_t* row = V + seq_off_ch(seq0 + b) + (size_t)c * LS + XPAD + p;
;                 raws[it] = *(const u32x4*)row;
;                 const unsigned xm = p > 0 ? (unsigned)row[-1] : 0u, xp = (p + 8 < L) ? (unsigned)row[8] : 0u;
;                 halos[it] = xm | (xp << 16);
;             }
;         }
.LBB0_1249:
	s_or_b64 exec, exec, s[28:29]
	v_add_u32_e32 v42, 0xe00, v190
	s_mov_b32 s24, 0xe32943
	v_mul_hi_i32 v43, v42, s24
	v_lshrrev_b32_e32 v32, 31, v43
	v_ashrrev_i32_e32 v46, 1, v43
	v_add_u32_e32 v82, v46, v32
	v_mul_i32_i24_e32 v43, 0x241, v82
	v_sub_u32_e32 v83, v42, v43
	s_movk_i32 s24, 0x408
	v_subrev_u32_e32 v42, 28, v83
	s_movk_i32 s28, 0x202
	v_cmp_gt_i32_e64 s[24:25], s24, v190
	v_cmp_gt_u32_e64 s[42:43], s28, v42
	s_and_b64 s[28:29], s[24:25], s[42:43]
	v_mov_b32_e32 v45, 0
	v_mov_b32_e32 v44, 0
	v_mov_b32_e32 v43, 0
	v_mov_b32_e32 v42, 0
	v_mov_b32_e32 v95, 0
	s_and_saveexec_b64 s[34:35], s[28:29]
	s_cbranch_execz .LBB0_1259
	v_add3_u32 v32, v46, v32, s50
	v_cmp_lt_i32_e64 s[28:29], 3, v32
	s_and_saveexec_b64 s[44:45], s[28:29]
	s_xor_b64 s[28:29], exec, s[44:45]
	v_add_u32_e32 v32, -4, v32
	s_mov_b32 s44, 0x410000
	v_mov_b64_e32 v[42:43], 0x2040000
	v_mad_u64_u32 v[42:43], s[44:45], v32, s44, v[42:43]
	s_andn2_saveexec_b64 s[28:29], s[28:29]
	s_mov_b32 s44, 0x810000
	v_mad_i64_i32 v[42:43], s[44:45], v32, s44, 0
	s_or_b64 exec, exec, s[28:29]
	v_lshl_add_u64 v[42:43], v[42:43], 1, s[70:71]
	v_lshlrev_b32_e32 v32, 4, v83
	v_lshl_add_u64 v[46:47], v[42:43], 0, v[32:33]
	global_load_dwordx4 v[42:45], v[46:47], off offset:-352
	v_cmp_lt_u32_e64 s[28:29], 28, v83
	v_mov_b32_e32 v48, 0
	v_mov_b32_e32 v32, 0
	s_and_saveexec_b64 s[44:45], s[28:29]
	s_cbranch_execz .LBB0_1256
	global_load_ushort v124, v[46:47], off offset:-354
.LBB0_1256:
	s_or_b64 exec, exec, s[44:45]
	s_movk_i32 s28, 0x21d
	v_cmp_gt_u32_e64 s[28:29], s28, v83
	s_and_saveexec_b64 s[44:45], s[28:29]
	s_cbranch_execz .LBB0_1258
	global_load_ushort v125, v[46:47], off offset:-336

; template <int NQ, int NB, int L>
; __device__ __forceinline__ void conv_unit(LAS unsigned char* lds, const Args& a, int j, int seq0, int c, int tid) {
;     ...
; #pragma unroll
;         for (int it = 0; it < NIT; ++it) {
;             const int idx = it * 512 + tid; const int b = idx / NCH, ch = idx % NCH, p = ch * 8 - PADL;
;             raws[it] = (u32x4){0u, 0u, 0u, 0u}; halos[it] = 0u;
;             if (idx < NB * NCH && p >= 0 && p < L) {
;                 const bf16_t* row = V + seq_off_ch(seq0 + b) + (size_t)c * LS + XPAD + p;
;                 raws[it] = *(const u32x4*)row;
;                 const unsigned xm = p > 0 ? (unsigned)row[-1] : 0u, xp = (p + 8 < L) ? (unsigned)row[8] : 0u;
;                 halos[it] = xm | (xp << 16);
;             }
;         }
.LBB0_1259:
	s_or_b64 exec, exec, s[34:35]
	v_add_u32_e32 v46, 0x1000, v190
	s_mov_b32 s28, 0xe32943
	v_mul_hi_i32 v47, v46, s28
	v_lshrrev_b32_e32 v32, 31, v47
	v_ashrrev_i32_e32 v50, 1, v47
	v_add_u32_e32 v85, v50, v32
	v_mul_i32_i24_e32 v47, 0x241, v85
	v_sub_u32_e32 v86, v46, v47
	s_movk_i32 s28, 0x208
	v_subrev_u32_e32 v46, 28, v86
	s_movk_i32 s34, 0x202
	v_cmp_gt_i32_e64 s[28:29], s28, v190
	v_cmp_gt_u32_e64 s[44:45], s34, v46
	s_and_b64 s[34:35], s[28:29], s[44:45]
	v_mov_b32_e32 v49, 0
	v_mov_b32_e32 v48, 0
	v_mov_b32_e32 v47, 0
	v_mov_b32_e32 v46, 0
	v_mov_b32_e32 v96, 0
	s_and_saveexec_b64 s[46:47], s[34:35]
	s_cbranch_execz .LBB0_1269
	v_add3_u32 v32, v50, v32, s50
	v_cmp_lt_i32_e64 s[34:35], 3, v32
	s_and_saveexec_b64 s[48:49], s[34:35]
	s_xor_b64 s[34:35], exec, s[48:49]
	v_add_u32_e32 v32, -4, v32
	s_mov_b32 s48, 0x410000
	v_mov_b64_e32 v[46:47], 0x2040000
	v_mad_u64_u32 v[46:47], s[48:49], v32, s48, v[46:47]
	s_andn2_saveexec_b64 s[34:35], s[34:35]
	s_mov_b32 s48, 0x810000
	v_mad_i64_i32 v[46:47], s[48:49], v32, s48, 0
	s_or_b64 exec, exec, s[34:35]
	v_lshl_add_u64 v[46:47], v[46:47], 1, s[70:71]
	v_lshlrev_b32_e32 v32, 4, v86
	v_lshl_add_u64 v[50:51], v[46:47], 0, v[32:33]
	global_load_dwordx4 v[46:49], v[50:51], off offset:-352
	v_cmp_lt_u32_e64 s[34:35], 28, v86
	v_mov_b32_e32 v52, 0
	v_mov_b32_e32 v32, 0
	s_and_saveexec_b64 s[48:49], s[34:35]
	s_cbranch_execz .LBB0_1266
	global_load_ushort v126, v[50:51], off offset:-354
.LBB0_1266:
	s_or_b64 exec, exec, s[48:49]
	s_movk_i32 s34, 0x21d
	v_cmp_gt_u32_e64 s[34:35], s34, v86
	s_and_saveexec_b64 s[48:49], s[34:35]
	s_cbranch_execz .LBB0_1268
	global_load_ushort v127, v[50:51], off offset:-336

; template <int NQ, int NB, int L>
; __device__ __forceinline__ void conv_unit(LAS unsigned char* lds, const Args& a, int j, int seq0, int c, int tid) {
;     ...
; #pragma unroll
;         for (int it = 0; it < NIT; ++it) {
;             const int idx = it * 512 + tid; const int b = idx / NCH, ch = idx % NCH, p = ch * 8 - PADL;
;             raws[it] = (u32x4){0u, 0u, 0u, 0u}; halos[it] = 0u;
;             if (idx < NB * NCH && p >= 0 && p < L) {
;                 const bf16_t* row = V + seq_off_ch(seq0 + b) + (size_t)c * LS + XPAD + p;
;                 raws[it] = *(const u32x4*)row;
;                 const unsigned xm = p > 0 ? (unsigned)row[-1] : 0u, xp = (p + 8 < L) ? (unsigned)row[8] : 0u;
;                 halos[it] = xm | (xp << 16);
;             }
;         }
.LBB0_1269:
	s_or_b64 exec, exec, s[46:47]
	v_add_u32_e32 v32, 0x1200, v190
	s_mov_b32 s34, 0xe32943
	v_mul_hi_i32 v50, v32, s34
	v_lshrrev_b32_e32 v54, 31, v50
	v_ashrrev_i32_e32 v55, 1, v50
	v_add_u32_e32 v88, v55, v54
	v_mul_i32_i24_e32 v50, 0x241, v88
	v_sub_u32_e32 v89, v32, v50
	v_subrev_u32_e32 v32, 28, v89
	s_movk_i32 s46, 0x202
	v_cmp_gt_i32_e64 s[34:35], 8, v190
	v_cmp_gt_u32_e64 s[46:47], s46, v32
	s_and_b64 s[48:49], s[34:35], s[46:47]
	v_mov_b32_e32 v53, 0
	v_mov_b32_e32 v52, 0
	v_mov_b32_e32 v51, 0
	v_mov_b32_e32 v50, 0
	v_mov_b32_e32 v32, 0
	s_and_saveexec_b64 s[72:73], s[48:49]
	s_cbranch_execz .LBB0_1279
	v_add3_u32 v32, v55, v54, s50
	v_cmp_lt_i32_e64 s[48:49], 3, v32
	s_and_saveexec_b64 s[50:51], s[48:49]
	s_xor_b64 s[48:49], exec, s[50:51]
	v_add_u32_e32 v32, -4, v32
	s_mov_b32 s50, 0x410000
	v_mov_b64_e32 v[50:51], 0x2040000
	v_mad_u64_u32 v[50:51], s[50:51], v32, s50, v[50:51]
	s_andn2_saveexec_b64 s[48:49], s[48:49]
	s_mov_b32 s50, 0x810000
	v_mad_i64_i32 v[50:51], s[50:51], v32, s50, 0
	s_or_b64 exec, exec, s[48:49]
	v_lshl_add_u64 v[50:51], v[50:51], 1, s[70:71]
	v_lshlrev_b32_e32 v32, 4, v89
	v_lshl_add_u64 v[54:55], v[50:51], 0, v[32:33]
	global_load_dwordx4 v[50:53], v[54:55], off offset:-352
	v_cmp_lt_u32_e64 s[48:49], 28, v89
	v_mov_b32_e32 v56, 0
	v_mov_b32_e32 v32, 0
	s_and_saveexec_b64 s[70:71], s[48:49]
	s_cbranch_execz .LBB0_1276
	global_load_ushort v128, v[54:55], off offset:-354
.LBB0_1276:
	s_or_b64 exec, exec, s[70:71]
	s_movk_i32 s48, 0x21d
	v_cmp_gt_u32_e64 s[48:49], s48, v89
	s_and_saveexec_b64 s[70:71], s[48:49]
	s_cbranch_execz .LBB0_1278
	global_load_ushort v129, v[54:55], off offset:-336

; __device__ __forceinline__ unsigned cvtpk(float lo, float hi) { f32x2 v = {lo, hi}; bf16x2_t b = __builtin_convertvector(v, bf16x2_t); return __builtin_bit_cast(unsigned, b); }
; template <int NQ, int NB, int L>
; __device__ __forceinline__ void conv_unit(LAS unsigned char* lds, const Args& a, int j, int seq0, int c, int tid) {
;     ...
;                 const unsigned xm = p > 0 ? (unsigned)row[-1] : 0u, xp = (p + 8 < L) ? (unsigned)row[8] : 0u;
;                 halos[it] = xm | (xp << 16);
;             }
;         }
; #pragma unroll
;         for (int it = 0; it < NIT; ++it) {
;             const int idx = it * 512 + tid; const int b = idx / NCH, ch = idx % NCH, p = ch * 8 - PADL;
;             u32x4 o = {0u, 0u, 0u, 0u};
;             if (p >= 0 && p < L) {
;                 const u32x4 raw = raws[it];
;                 float x[10];
;                 x[0] = bflo(halos[it]); x[9] = bfhi(halos[it]);
;                 x[1] = bflo(raw.x); x[2] = bfhi(raw.x); x[3] = bflo(raw.y); x[4] = bfhi(raw.y); x[5] = bflo(raw.z); x[6] = bfhi(raw.z); x[7] = bflo(raw.w); x[8] = bfhi(raw.w);
;                 float y[8];
; #pragma unroll
;                 for (int i = 0; i < 8; ++i) y[i] = w0 * x[i] + w1 * x[i + 1] + w2 * x[i + 2] + bb;
;                 o.x = cvtpk(y[0], y[1]); o.y = cvtpk(y[2], y[3]); o.z = cvtpk(y[4], y[5]); o.w = cvtpk(y[6], y[7]);
.LBB0_1279:
	s_or_b64 exec, exec, s[72:73]
	s_waitcnt vmcnt(0)
	v_lshl_or_b32 v84, v111, 16, v110
	v_lshl_or_b32 v87, v113, 16, v112
	v_lshl_or_b32 v90, v115, 16, v114
	v_lshl_or_b32 v91, v117, 16, v116
	v_lshl_or_b32 v92, v119, 16, v118
	v_lshl_or_b32 v93, v121, 16, v120
	v_lshl_or_b32 v94, v123, 16, v122
	v_lshl_or_b32 v95, v125, 16, v124
	v_lshl_or_b32 v96, v127, 16, v126
	v_lshl_or_b32 v32, v129, 16, v128
	v_mov_b32_e32 v54, 0
	v_mov_b32_e32 v55, 0
	v_mov_b32_e32 v56, 0
	v_mov_b32_e32 v57, 0
	s_and_saveexec_b64 s[48:49], s[18:19]
	s_cbranch_execz .LBB0_1281
	v_and_b32_e32 v104, 0xffff0000, v12
	v_and_b32_e32 v103, 16, v14
	v_and_b32_e32 v102, 0xffff0000, v13
	v_lshlrev_b32_e32 v107, 16, v13
	v_mov_b32_e32 v106, v104
	v_and_b32_e32 v55, 16, v15
	v_and_b32_e32 v54, 0xffff0000, v14
	v_lshlrev_b32_e32 v57, 16, v15
	v_and_b32_e32 v98, 0xffff0000, v15
	v_lshlrev_b32_e32 v15, 16, v14
	v_mov_b32_e32 v14, v102
	v_pk_mov_b32 v[102:103], v[106:107], v[102:103] op_sel:[1,0]
	v_mov_b32_e32 v56, v54
	v_and_b32_e32 v99, 0xffff0000, v84
	v_and_b32_e32 v105, 16, v13
	v_lshlrev_b32_e32 v13, 16, v12
	v_lshlrev_b32_e32 v12, 16, v84
	s_waitcnt vmcnt(4)
	v_pk_mul_f32 v[102:103], v[66:67], v[102:103] op_sel_hi:[0,1]
	v_pk_mov_b32 v[54:55], v[14:15], v[54:55] op_sel:[1,0]
	v_pk_mov_b32 v[100:101], v[56:57], v[98:99] op_sel:[1,0]
	v_pk_mov_b32 v[104:105], v[12:13], v[104:105] op_sel:[1,0]
	s_waitcnt vmcnt(1)
	v_pk_fma_f32 v[102:103], v[68:69], v[106:107], v[102:103] op_sel_hi:[0,1,1]
	v_pk_mul_f32 v[54:55], v[66:67], v[54:55] op_sel_hi:[0,1]
	v_pk_mul_f32 v[104:105], v[66:67], v[104:105] op_sel_hi:[0,1]
	v_pk_fma_f32 v[102:103], v[64:65], v[14:15], v[102:103] op_sel_hi:[0,1,1]
	v_pk_fma_f32 v[14:15], v[68:69], v[14:15], v[54:55] op_sel_hi:[0,1,1]
	v_pk_mul_f32 v[54:55], v[66:67], v[100:101] op_sel_hi:[0,1]
	v_pk_fma_f32 v[12:13], v[68:69], v[12:13], v[104:105] op_sel_hi:[0,1,1]
	v_pk_fma_f32 v[54:55], v[68:69], v[56:57], v[54:55] op_sel_hi:[0,1,1]
	v_pk_fma_f32 v[12:13], v[64:65], v[106:107], v[12:13] op_sel_hi:[0,1,1]
	v_pk_fma_f32 v[14:15], v[64:65], v[56:57], v[14:15] op_sel_hi:[0,1,1]
	v_pk_fma_f32 v[54:55], v[64:65], v[98:99], v[54:55] op_sel_hi:[0,1,1]
	s_waitcnt vmcnt(0)
	v_pk_add_f32 v[12:13], v[70:71], v[12:13] op_sel_hi:[0,1]
	v_pk_add_f32 v[102:103], v[70:71], v[102:103] op_sel_hi:[0,1]
	v_pk_add_f32 v[14:15], v[70:71], v[14:15] op_sel_hi:[0,1]
	v_pk_add_f32 v[98:99], v[70:71], v[54:55] op_sel_hi:[0,1]
	v_cvt_pk_bf16_f32 v54, v12, v13
	v_cvt_pk_bf16_f32 v55, v102, v103
	v_cvt_pk_bf16_f32 v56, v14, v15
	v_cvt_pk_bf16_f32 v57, v98, v99

; template <int NQ, int NB, int L>
; __device__ __forceinline__ void conv_unit(LAS unsigned char* lds, const Args& a, int j, int seq0, int c, int tid) {
;     ...
;     {
;         const u32x4* src = (const u32x4*)(FK + (size_t)c * LEN);
; #pragma unroll
;         for (int it = 0; it < NF; ++it) { const int i = it * 512 + tid; fkr[it] = src[i < LEN / 8 ? i : 0]; }
;     }
;     {
;         const float w0 = cw[2048 + c], w1 = cw[3072 + 2048 + c], w2 = cw[2 * 3072 + 2048 + c], bb = cb[2048 + c];
;         constexpr int NCH = LPD / 8, NIT = (NB * NCH + 511) / 512;
;         u32x4 raws[NIT]; unsigned halos[NIT];
; #pragma unroll
;         for (int it = 0; it < NIT; ++it) {
;             const int idx = it * 512 + tid; const int b = idx / NCH, ch = idx % NCH, p = ch * 8 - PADL;
;             raws[it] = (u32x4){0u, 0u, 0u, 0u}; halos[it] = 0u;
;             if (idx < NB * NCH && p >= 0 && p < L) {
;                 const bf16_t* row = V + seq_off_ch(seq0 + b) + (size_t)c * LS + XPAD + p;
;                 raws[it] = *(const u32x4*)row;
;                 const unsigned xm = p > 0 ? (unsigned)row[-1] : 0u, xp = (p + 8 < L) ? (unsigned)row[8] : 0u;
;                 halos[it] = xm | (xp << 16);
;             }
;         }
.LBB0_1429:
	v_mov_b32_e32 v120, 0
	v_mov_b32_e32 v121, 0
	v_mov_b32_e32 v122, 0
	v_mov_b32_e32 v123, 0
	v_mov_b32_e32 v124, 0
	v_mov_b32_e32 v125, 0
	v_mov_b32_e32 v126, 0
	v_mov_b32_e32 v127, 0
	v_mov_b32_e32 v128, 0
	v_mov_b32_e32 v129, 0
	v_mov_b32_e32 v130, 0
	v_mov_b32_e32 v131, 0
	v_mov_b32_e32 v132, 0
	v_mov_b32_e32 v133, 0
	v_mov_b32_e32 v134, 0
	v_mov_b32_e32 v135, 0
	v_mov_b32_e32 v136, 0
	v_mov_b32_e32 v137, 0
	s_and_b64 vcc, exec, s[2:3]
	s_cbranch_vccz .LBB0_1177
	s_ashr_i32 s53, s52, 31
	s_mul_i32 s3, s52, 0x8800
	v_readlane_b32 s4, v254, 23
	s_mul_hi_i32 s2, s52, 0x8800
	s_add_u32 s72, s4, s3
	v_readlane_b32 s3, v254, 25
	s_addc_u32 s73, s3, s2
	s_movk_i32 s2, 0x880
	v_cmp_gt_i32_e64 s[4:5], s2, v190
	s_movk_i32 s2, 0x680
	v_cmp_gt_i32_e64 s[6:7], s2, v190
	s_movk_i32 s2, 0x480
	v_cmp_gt_i32_e64 s[8:9], s2, v190
	s_movk_i32 s2, 0x280
	v_cmp_gt_i32_e64 s[10:11], s2, v190
	s_movk_i32 s2, 0x80
	v_cmp_gt_i32_e64 s[12:13], s2, v190
	s_lshl_b64 s[2:3], s[52:53], 2
	s_add_u32 s16, s2, 0x2000
	s_addc_u32 s17, s3, 0
	v_add_u32_e32 v73, 0x600, v190
	s_add_u32 s14, s87, s16
	v_cndmask_b32_e64 v62, 0, v190, s[4:5]
	v_cndmask_b32_e64 v64, 0, v191, s[6:7]
	v_cndmask_b32_e64 v66, 0, v192, s[8:9]
	v_cndmask_b32_e64 v68, 0, v73, s[10:11]
	v_add_u32_e32 v75, 0x800, v190
	s_addc_u32 s15, s88, s17
	v_ashrrev_i32_e32 v63, 31, v62
	v_ashrrev_i32_e32 v65, 31, v64
	v_ashrrev_i32_e32 v67, 31, v66
	v_ashrrev_i32_e32 v69, 31, v68
	v_cndmask_b32_e64 v70, 0, v75, s[12:13]
	s_add_u32 s62, s87, s2
	v_lshl_add_u64 v[0:1], v[62:63], 4, s[72:73]
	v_lshl_add_u64 v[4:5], v[64:65], 4, s[72:73]
	v_lshl_add_u64 v[8:9], v[66:67], 4, s[72:73]
	v_lshl_add_u64 v[12:13], v[68:69], 4, s[72:73]
	v_ashrrev_i32_e32 v71, 31, v70
	s_addc_u32 s63, s88, s3
	v_mov_b32_e32 v20, 0x5000
	v_mov_b32_e32 v31, 0
	global_load_dwordx4 v[0:3], v[0:1], off
	s_nop 0
	global_load_dwordx4 v[4:7], v[4:5], off
	s_nop 0
	global_load_dwordx4 v[8:11], v[8:9], off
	s_nop 0
	global_load_dwordx4 v[12:15], v[12:13], off
	v_lshl_add_u64 v[16:17], v[70:71], 4, s[72:73]
	global_load_dword v74, v20, s[62:63]
	v_mov_b32_e32 v20, 0x8000
	s_add_u32 s2, s89, s16
	global_load_dwordx4 v[16:19], v[16:17], off
	s_addc_u32 s3, s90, s17
	global_load_dword v72, v20, s[62:63]
	global_load_dword v76, v31, s[14:15]
	global_load_dword v78, v31, s[2:3]
	s_mul_i32 s3, s52, 0x4080
	s_mul_hi_i32 s2, s52, 0x4080
	s_add_u32 s48, s58, s3
	s_addc_u32 s49, s59, s2
	s_mov_b32 s2, 0xf07fc3e1
	v_mul_hi_i32 v20, v190, s2
	v_add_u32_e32 v20, v20, v190
	v_lshrrev_b32_e32 v21, 31, v20
	v_ashrrev_i32_e32 v20, 10, v20
	v_add_u32_e32 v97, v20, v21
	v_mul_i32_i24_e32 v20, 0x442, v97
	v_sub_u32_e32 v22, v190, v20
	s_movk_i32 s2, 0x1108
	v_cmp_gt_i32_e64 s[36:37], s2, v190
	v_subrev_u32_e32 v20, 28, v22
	s_movk_i32 s2, 0x402
	v_cmp_gt_u32_e64 s[46:47], s2, v20
	v_readfirstlane_b32 s51, v190
	s_and_b64 s[14:15], s[36:37], s[46:47]
	v_lshlrev_b32_e32 v32, 4, v22
	v_mov_b32_e32 v30, 0
	v_mov_b32_e32 v29, 0
	v_mov_b32_e32 v28, 0
	v_mov_b32_e32 v103, 0
	s_and_saveexec_b64 s[2:3], s[14:15]
	s_cbranch_execz .LBB0_1436
	v_mov_b64_e32 v[20:21], s[48:49]
	s_mov_b32 s14, 0x1020000
	v_mad_i64_i32 v[20:21], s[14:15], v97, s14, v[20:21]
	v_lshl_add_u64 v[20:21], v[20:21], 0, v[32:33]
	global_load_dwordx4 v[28:31], v[20:21], off offset:-352
	v_cmp_lt_u32_e32 vcc, 28, v22
	v_mov_b32_e32 v24, 0
	v_mov_b32_e32 v23, 0
	s_and_saveexec_b64 s[14:15], vcc
	s_cbranch_execz .LBB0_1433
	global_load_ushort v120, v[20:21], off offset:-354
.LBB0_1433:
	s_or_b64 exec, exec, s[14:15]
	s_movk_i32 s14, 0x41d
	v_cmp_gt_u32_e32 vcc, s14, v22
	s_and_saveexec_b64 s[14:15], vcc
	s_cbranch_execz .LBB0_1435
	global_load_ushort v121, v[20:21], off offset:-336

; template <int NQ, int NB, int L>
; __device__ __forceinline__ void conv_unit(LAS unsigned char* lds, const Args& a, int j, int seq0, int c, int tid) {
;     ...
; #pragma unroll
;         for (int it = 0; it < NIT; ++it) {
;             const int idx = it * 512 + tid; const int b = idx / NCH, ch = idx % NCH, p = ch * 8 - PADL;
;             raws[it] = (u32x4){0u, 0u, 0u, 0u}; halos[it] = 0u;
;             if (idx < NB * NCH && p >= 0 && p < L) {
;                 const bf16_t* row = V + seq_off_ch(seq0 + b) + (size_t)c * LS + XPAD + p;
;                 raws[it] = *(const u32x4*)row;
;                 const unsigned xm = p > 0 ? (unsigned)row[-1] : 0u, xp = (p + 8 < L) ? (unsigned)row[8] : 0u;
;                 halos[it] = xm | (xp << 16);
;             }
;         }
.LBB0_1436:
	s_or_b64 exec, exec, s[2:3]
	s_mov_b32 s2, 0xf07fc3e1
	v_mul_hi_i32 v20, v191, s2
	v_add_u32_e32 v20, v20, v191
	v_lshrrev_b32_e32 v21, 31, v20
	v_ashrrev_i32_e32 v20, 10, v20
	v_add_u32_e32 v96, v20, v21
	v_mul_i32_i24_e32 v20, 0x442, v96
	v_sub_u32_e32 v22, v191, v20
	s_movk_i32 s2, 0xf08
	v_cmp_gt_i32_e64 s[30:31], s2, v190
	v_subrev_u32_e32 v20, 28, v22
	s_movk_i32 s2, 0x402
	v_cmp_gt_u32_e64 s[44:45], s2, v20
	s_and_b64 s[14:15], s[30:31], s[44:45]
	v_mov_b32_e32 v57, 0
	v_lshlrev_b32_e32 v94, 4, v22
	v_mov_b32_e32 v56, 0
	v_mov_b32_e32 v55, 0
	v_mov_b32_e32 v54, 0
	v_mov_b32_e32 v102, 0
	s_and_saveexec_b64 s[2:3], s[14:15]
	s_cbranch_execz .LBB0_1442
	v_mov_b64_e32 v[20:21], s[48:49]
	s_mov_b32 s14, 0x1020000
	v_mad_i64_i32 v[20:21], s[14:15], v96, s14, v[20:21]
	v_mov_b32_e32 v95, v33
	v_lshl_add_u64 v[20:21], v[20:21], 0, v[94:95]
	global_load_dwordx4 v[54:57], v[20:21], off offset:-352
	v_cmp_lt_u32_e32 vcc, 28, v22
	v_mov_b32_e32 v24, 0
	v_mov_b32_e32 v23, 0
	s_and_saveexec_b64 s[14:15], vcc
	s_cbranch_execz .LBB0_1439
	global_load_ushort v122, v[20:21], off offset:-354
.LBB0_1439:
	s_or_b64 exec, exec, s[14:15]
	s_movk_i32 s14, 0x41d
	v_cmp_gt_u32_e32 vcc, s14, v22
	s_and_saveexec_b64 s[14:15], vcc
	s_cbranch_execz .LBB0_1441
	global_load_ushort v123, v[20:21], off offset:-336

; template <int NQ, int NB, int L>
; __device__ __forceinline__ void conv_unit(LAS unsigned char* lds, const Args& a, int j, int seq0, int c, int tid) {
;     ...
; #pragma unroll
;         for (int it = 0; it < NIT; ++it) {
;             const int idx = it * 512 + tid; const int b = idx / NCH, ch = idx % NCH, p = ch * 8 - PADL;
;             raws[it] = (u32x4){0u, 0u, 0u, 0u}; halos[it] = 0u;
;             if (idx < NB * NCH && p >= 0 && p < L) {
;                 const bf16_t* row = V + seq_off_ch(seq0 + b) + (size_t)c * LS + XPAD + p;
;                 raws[it] = *(const u32x4*)row;
;                 const unsigned xm = p > 0 ? (unsigned)row[-1] : 0u, xp = (p + 8 < L) ? (unsigned)row[8] : 0u;
;                 halos[it] = xm | (xp << 16);
;             }
;         }
.LBB0_1442:
	s_or_b64 exec, exec, s[2:3]
	s_mov_b32 s2, 0xf07fc3e1
	v_mul_hi_i32 v20, v192, s2
	v_add_u32_e32 v20, v20, v192
	v_lshrrev_b32_e32 v21, 31, v20
	v_ashrrev_i32_e32 v20, 10, v20
	v_add_u32_e32 v95, v20, v21
	v_mul_i32_i24_e32 v20, 0x442, v95
	v_sub_u32_e32 v22, v192, v20
	s_movk_i32 s2, 0xd08
	v_cmp_gt_i32_e64 s[26:27], s2, v190
	v_subrev_u32_e32 v20, 28, v22
	s_movk_i32 s2, 0x402
	v_cmp_gt_u32_e64 s[42:43], s2, v20
	s_and_b64 s[14:15], s[26:27], s[42:43]
	v_mov_b32_e32 v53, 0
	v_lshlrev_b32_e32 v92, 4, v22
	v_mov_b32_e32 v52, 0
	v_mov_b32_e32 v51, 0
	v_mov_b32_e32 v50, 0
	v_mov_b32_e32 v101, 0
	s_and_saveexec_b64 s[2:3], s[14:15]
	s_cbranch_execz .LBB0_1448
	v_mov_b64_e32 v[20:21], s[48:49]
	s_mov_b32 s14, 0x1020000
	v_mad_i64_i32 v[20:21], s[14:15], v95, s14, v[20:21]
	v_mov_b32_e32 v93, v33
	v_lshl_add_u64 v[20:21], v[20:21], 0, v[92:93]
	global_load_dwordx4 v[50:53], v[20:21], off offset:-352
	v_cmp_lt_u32_e32 vcc, 28, v22
	v_mov_b32_e32 v24, 0
	v_mov_b32_e32 v23, 0
	s_and_saveexec_b64 s[14:15], vcc
	s_cbranch_execz .LBB0_1445
	global_load_ushort v124, v[20:21], off offset:-354
.LBB0_1445:
	s_or_b64 exec, exec, s[14:15]
	s_movk_i32 s14, 0x41d
	v_cmp_gt_u32_e32 vcc, s14, v22
	s_and_saveexec_b64 s[14:15], vcc
	s_cbranch_execz .LBB0_1447
	global_load_ushort v125, v[20:21], off offset:-336

; template <int NQ, int NB, int L>
; __device__ __forceinline__ void conv_unit(LAS unsigned char* lds, const Args& a, int j, int seq0, int c, int tid) {
;     ...
; #pragma unroll
;         for (int it = 0; it < NIT; ++it) {
;             const int idx = it * 512 + tid; const int b = idx / NCH, ch = idx % NCH, p = ch * 8 - PADL;
;             raws[it] = (u32x4){0u, 0u, 0u, 0u}; halos[it] = 0u;
;             if (idx < NB * NCH && p >= 0 && p < L) {
;                 const bf16_t* row = V + seq_off_ch(seq0 + b) + (size_t)c * LS + XPAD + p;
;                 raws[it] = *(const u32x4*)row;
;                 const unsigned xm = p > 0 ? (unsigned)row[-1] : 0u, xp = (p + 8 < L) ? (unsigned)row[8] : 0u;
;                 halos[it] = xm | (xp << 16);
;             }
;         }
.LBB0_1448:
	s_or_b64 exec, exec, s[2:3]
	s_mov_b32 s2, 0xf07fc3e1
	v_mul_hi_i32 v20, v73, s2
	v_add_u32_e32 v20, v20, v73
	v_lshrrev_b32_e32 v21, 31, v20
	v_ashrrev_i32_e32 v20, 10, v20
	v_add_u32_e32 v93, v20, v21
	v_mul_i32_i24_e32 v20, 0x442, v93
	v_sub_u32_e32 v22, v73, v20
	s_movk_i32 s2, 0xb08
	v_cmp_gt_i32_e64 s[22:23], s2, v190
	v_subrev_u32_e32 v20, 28, v22
	s_movk_i32 s2, 0x402
	v_cmp_gt_u32_e64 s[40:41], s2, v20
	s_and_b64 s[14:15], s[22:23], s[40:41]
	v_mov_b32_e32 v49, 0
	v_lshlrev_b32_e32 v90, 4, v22
	v_mov_b32_e32 v48, 0
	v_mov_b32_e32 v47, 0
	v_mov_b32_e32 v46, 0
	v_mov_b32_e32 v100, 0
	s_and_saveexec_b64 s[2:3], s[14:15]
	s_cbranch_execz .LBB0_1454
	v_mov_b64_e32 v[20:21], s[48:49]
	s_mov_b32 s14, 0x1020000
	v_mad_i64_i32 v[20:21], s[14:15], v93, s14, v[20:21]
	v_mov_b32_e32 v91, v33
	v_lshl_add_u64 v[20:21], v[20:21], 0, v[90:91]
	global_load_dwordx4 v[46:49], v[20:21], off offset:-352
	v_cmp_lt_u32_e32 vcc, 28, v22
	v_mov_b32_e32 v24, 0
	v_mov_b32_e32 v23, 0
	s_and_saveexec_b64 s[14:15], vcc
	s_cbranch_execz .LBB0_1451
	global_load_ushort v126, v[20:21], off offset:-354
.LBB0_1451:
	s_or_b64 exec, exec, s[14:15]
	s_movk_i32 s14, 0x41d
	v_cmp_gt_u32_e32 vcc, s14, v22
	s_and_saveexec_b64 s[14:15], vcc
	s_cbranch_execz .LBB0_1453
	global_load_ushort v127, v[20:21], off offset:-336

; template <int NQ, int NB, int L>
; __device__ __forceinline__ void conv_unit(LAS unsigned char* lds, const Args& a, int j, int seq0, int c, int tid) {
;     ...
; #pragma unroll
;         for (int it = 0; it < NIT; ++it) {
;             const int idx = it * 512 + tid; const int b = idx / NCH, ch = idx % NCH, p = ch * 8 - PADL;
;             raws[it] = (u32x4){0u, 0u, 0u, 0u}; halos[it] = 0u;
;             if (idx < NB * NCH && p >= 0 && p < L) {
;                 const bf16_t* row = V + seq_off_ch(seq0 + b) + (size_t)c * LS + XPAD + p;
;                 raws[it] = *(const u32x4*)row;
;                 const unsigned xm = p > 0 ? (unsigned)row[-1] : 0u, xp = (p + 8 < L) ? (unsigned)row[8] : 0u;
;                 halos[it] = xm | (xp << 16);
;             }
.LBB0_1454:
	s_or_b64 exec, exec, s[2:3]
	s_mov_b32 s2, 0xf07fc3e1
	v_mul_hi_i32 v20, v75, s2
	v_add_u32_e32 v20, v20, v75
	v_lshrrev_b32_e32 v21, 31, v20
	v_ashrrev_i32_e32 v20, 10, v20
	v_add_u32_e32 v91, v20, v21
	v_mul_i32_i24_e32 v20, 0x442, v91
	v_sub_u32_e32 v22, v75, v20
	s_movk_i32 s2, 0x908
	v_cmp_gt_i32_e64 s[18:19], s2, v190
	v_subrev_u32_e32 v20, 28, v22
	s_movk_i32 s2, 0x402
	v_cmp_gt_u32_e64 s[38:39], s2, v20
	s_and_b64 s[14:15], s[18:19], s[38:39]
	v_mov_b32_e32 v45, 0
	v_lshlrev_b32_e32 v88, 4, v22
	v_mov_b32_e32 v44, 0
	v_mov_b32_e32 v43, 0
	v_mov_b32_e32 v42, 0
	v_mov_b32_e32 v99, 0
	s_and_saveexec_b64 s[2:3], s[14:15]
	s_cbranch_execz .LBB0_1460
	v_mov_b64_e32 v[20:21], s[48:49]
	s_mov_b32 s14, 0x1020000
	v_mad_i64_i32 v[20:21], s[14:15], v91, s14, v[20:21]
	v_mov_b32_e32 v89, v33
	v_lshl_add_u64 v[20:21], v[20:21], 0, v[88:89]
	global_load_dwordx4 v[42:45], v[20:21], off offset:-352
	v_cmp_lt_u32_e32 vcc, 28, v22
	v_mov_b32_e32 v24, 0
	v_mov_b32_e32 v23, 0
	s_and_saveexec_b64 s[14:15], vcc
	s_cbranch_execz .LBB0_1457
	global_load_ushort v128, v[20:21], off offset:-354
.LBB0_1457:
	s_or_b64 exec, exec, s[14:15]
	s_movk_i32 s14, 0x41d
	v_cmp_gt_u32_e32 vcc, s14, v22
	s_and_saveexec_b64 s[14:15], vcc
	s_cbranch_execz .LBB0_1459
	global_load_ushort v129, v[20:21], off offset:-336

; template <int NQ, int NB, int L>
; __device__ __forceinline__ void conv_unit(LAS unsigned char* lds, const Args& a, int j, int seq0, int c, int tid) {
;     ...
; #pragma unroll
;         for (int it = 0; it < NIT; ++it) {
;             const int idx = it * 512 + tid; const int b = idx / NCH, ch = idx % NCH, p = ch * 8 - PADL;
;             raws[it] = (u32x4){0u, 0u, 0u, 0u}; halos[it] = 0u;
;             if (idx < NB * NCH && p >= 0 && p < L) {
;                 const bf16_t* row = V + seq_off_ch(seq0 + b) + (size_t)c * LS + XPAD + p;
;                 raws[it] = *(const u32x4*)row;
;                 const unsigned xm = p > 0 ? (unsigned)row[-1] : 0u, xp = (p + 8 < L) ? (unsigned)row[8] : 0u;
;                 halos[it] = xm | (xp << 16);
;             }
.LBB0_1460:
	s_or_b64 exec, exec, s[2:3]
	v_add_u32_e32 v20, 0xa00, v190
	s_mov_b32 s2, 0xf07fc3e1
	v_mul_hi_i32 v21, v20, s2
	v_add_u32_e32 v21, v21, v20
	v_lshrrev_b32_e32 v22, 31, v21
	v_ashrrev_i32_e32 v21, 10, v21
	v_add_u32_e32 v89, v21, v22
	v_mul_i32_i24_e32 v21, 0x442, v89
	v_sub_u32_e32 v22, v20, v21
	s_movk_i32 s2, 0x708
	v_cmp_gt_i32_e64 s[16:17], s2, v190
	v_subrev_u32_e32 v20, 28, v22
	s_movk_i32 s2, 0x402
	v_cmp_gt_u32_e64 s[34:35], s2, v20
	s_and_b64 s[14:15], s[16:17], s[34:35]
	v_mov_b32_e32 v41, 0
	v_lshlrev_b32_e32 v86, 4, v22
	v_mov_b32_e32 v40, 0
	v_mov_b32_e32 v39, 0
	v_mov_b32_e32 v38, 0
	v_mov_b32_e32 v98, 0
	s_and_saveexec_b64 s[2:3], s[14:15]
	s_cbranch_execz .LBB0_1466
	v_mov_b64_e32 v[20:21], s[48:49]
	s_mov_b32 s14, 0x1020000
	v_mad_i64_i32 v[20:21], s[14:15], v89, s14, v[20:21]
	v_mov_b32_e32 v87, v33
	v_lshl_add_u64 v[20:21], v[20:21], 0, v[86:87]
	global_load_dwordx4 v[38:41], v[20:21], off offset:-352
	v_cmp_lt_u32_e32 vcc, 28, v22
	v_mov_b32_e32 v24, 0
	v_mov_b32_e32 v23, 0
	s_and_saveexec_b64 s[14:15], vcc
	s_cbranch_execz .LBB0_1463
	global_load_ushort v130, v[20:21], off offset:-354
.LBB0_1463:
	s_or_b64 exec, exec, s[14:15]
	s_movk_i32 s14, 0x41d
	v_cmp_gt_u32_e32 vcc, s14, v22
	s_and_saveexec_b64 s[14:15], vcc
	s_cbranch_execz .LBB0_1465
	global_load_ushort v131, v[20:21], off offset:-336

; template <int NQ, int NB, int L>
; __device__ __forceinline__ void conv_unit(LAS unsigned char* lds, const Args& a, int j, int seq0, int c, int tid) {
;     ...
; #pragma unroll
;         for (int it = 0; it < NIT; ++it) {
;             const int idx = it * 512 + tid; const int b = idx / NCH, ch = idx % NCH, p = ch * 8 - PADL;
;             raws[it] = (u32x4){0u, 0u, 0u, 0u}; halos[it] = 0u;
;             if (idx < NB * NCH && p >= 0 && p < L) {
;                 const bf16_t* row = V + seq_off_ch(seq0 + b) + (size_t)c * LS + XPAD + p;
;                 raws[it] = *(const u32x4*)row;
;                 const unsigned xm = p > 0 ? (unsigned)row[-1] : 0u, xp = (p + 8 < L) ? (unsigned)row[8] : 0u;
;                 halos[it] = xm | (xp << 16);
;             }
.LBB0_1466:
	s_or_b64 exec, exec, s[2:3]
	v_add_u32_e32 v20, 0xc00, v190
	s_mov_b32 s2, 0xf07fc3e1
	v_mul_hi_i32 v21, v20, s2
	v_add_u32_e32 v21, v21, v20
	v_lshrrev_b32_e32 v22, 31, v21
	v_ashrrev_i32_e32 v21, 10, v21
	v_add_u32_e32 v87, v21, v22
	v_mul_i32_i24_e32 v21, 0x442, v87
	v_sub_u32_e32 v22, v20, v21
	s_movk_i32 s2, 0x508
	v_cmp_gt_i32_e64 s[14:15], s2, v190
	v_subrev_u32_e32 v20, 28, v22
	s_movk_i32 s2, 0x402
	v_cmp_gt_u32_e64 s[28:29], s2, v20
	s_and_b64 s[20:21], s[14:15], s[28:29]
	v_mov_b32_e32 v37, 0
	v_lshlrev_b32_e32 v84, 4, v22
	v_mov_b32_e32 v36, 0
	v_mov_b32_e32 v35, 0
	v_mov_b32_e32 v34, 0
	v_mov_b32_e32 v85, 0
	s_and_saveexec_b64 s[2:3], s[20:21]
	s_cbranch_execz .LBB0_1472
	v_mov_b64_e32 v[20:21], s[48:49]
	s_mov_b32 s20, 0x1020000
	v_mad_i64_i32 v[20:21], s[20:21], v87, s20, v[20:21]
	v_mov_b32_e32 v85, v33
	v_lshl_add_u64 v[20:21], v[20:21], 0, v[84:85]
	global_load_dwordx4 v[34:37], v[20:21], off offset:-352
	v_cmp_lt_u32_e32 vcc, 28, v22
	v_mov_b32_e32 v24, 0
	v_mov_b32_e32 v23, 0
	s_and_saveexec_b64 s[20:21], vcc
	s_cbranch_execz .LBB0_1469
	global_load_ushort v132, v[20:21], off offset:-354
.LBB0_1469:
	s_or_b64 exec, exec, s[20:21]
	s_movk_i32 s20, 0x41d
	v_cmp_gt_u32_e32 vcc, s20, v22
	s_and_saveexec_b64 s[20:21], vcc
	s_cbranch_execz .LBB0_1471
	global_load_ushort v133, v[20:21], off offset:-336

; template <int NQ, int NB, int L>
; __device__ __forceinline__ void conv_unit(LAS unsigned char* lds, const Args& a, int j, int seq0, int c, int tid) {
;     ...
; #pragma unroll
;         for (int it = 0; it < NIT; ++it) {
;             const int idx = it * 512 + tid; const int b = idx / NCH, ch = idx % NCH, p = ch * 8 - PADL;
;             raws[it] = (u32x4){0u, 0u, 0u, 0u}; halos[it] = 0u;
;             if (idx < NB * NCH && p >= 0 && p < L) {
;                 const bf16_t* row = V + seq_off_ch(seq0 + b) + (size_t)c * LS + XPAD + p;
;                 raws[it] = *(const u32x4*)row;
;                 const unsigned xm = p > 0 ? (unsigned)row[-1] : 0u, xp = (p + 8 < L) ? (unsigned)row[8] : 0u;
;                 halos[it] = xm | (xp << 16);
;             }
.LBB0_1472:
	s_or_b64 exec, exec, s[2:3]
	v_add_u32_e32 v20, 0xe00, v190
	s_mov_b32 s2, 0xf07fc3e1
	v_mul_hi_i32 v21, v20, s2
	v_add_u32_e32 v21, v21, v20
	v_lshrrev_b32_e32 v22, 31, v21
	v_ashrrev_i32_e32 v21, 10, v21
	v_add_u32_e32 v79, v21, v22
	v_mul_i32_i24_e32 v21, 0x442, v79
	v_sub_u32_e32 v22, v20, v21
	s_movk_i32 s2, 0x308
	v_subrev_u32_e32 v20, 28, v22
	s_movk_i32 s20, 0x402
	v_cmp_gt_i32_e64 s[2:3], s2, v190
	v_cmp_gt_u32_e64 s[24:25], s20, v20
	s_and_b64 s[66:67], s[2:3], s[24:25]
	v_mov_b32_e32 v27, 0
	v_lshlrev_b32_e32 v82, 4, v22
	v_mov_b32_e32 v26, 0
	v_mov_b32_e32 v25, 0
	v_mov_b32_e32 v24, 0
	v_mov_b32_e32 v83, 0
	s_and_saveexec_b64 s[20:21], s[66:67]
	s_cbranch_execz .LBB0_1478
	v_mov_b64_e32 v[20:21], s[48:49]
	s_mov_b32 s50, 0x1020000
	v_mad_i64_i32 v[20:21], s[66:67], v79, s50, v[20:21]
	v_mov_b32_e32 v83, v33
	v_lshl_add_u64 v[20:21], v[20:21], 0, v[82:83]
	global_load_dwordx4 v[24:27], v[20:21], off offset:-352
	v_cmp_lt_u32_e32 vcc, 28, v22
	v_mov_b32_e32 v58, 0
	v_mov_b32_e32 v23, 0
	s_and_saveexec_b64 s[66:67], vcc
	s_cbranch_execz .LBB0_1475
	global_load_ushort v134, v[20:21], off offset:-354
.LBB0_1475:
	s_or_b64 exec, exec, s[66:67]
	s_movk_i32 s50, 0x41d
	v_cmp_gt_u32_e32 vcc, s50, v22
	s_and_saveexec_b64 s[66:67], vcc
	s_cbranch_execz .LBB0_1477
	global_load_ushort v135, v[20:21], off offset:-336

; template <int NQ, int NB, int L>
; __device__ __forceinline__ void conv_unit(LAS unsigned char* lds, const Args& a, int j, int seq0, int c, int tid) {
;     ...
; #pragma unroll
;         for (int it = 0; it < NIT; ++it) {
;             const int idx = it * 512 + tid; const int b = idx / NCH, ch = idx % NCH, p = ch * 8 - PADL;
;             raws[it] = (u32x4){0u, 0u, 0u, 0u}; halos[it] = 0u;
;             if (idx < NB * NCH && p >= 0 && p < L) {
;                 const bf16_t* row = V + seq_off_ch(seq0 + b) + (size_t)c * LS + XPAD + p;
;                 raws[it] = *(const u32x4*)row;
;                 const unsigned xm = p > 0 ? (unsigned)row[-1] : 0u, xp = (p + 8 < L) ? (unsigned)row[8] : 0u;
;                 halos[it] = xm | (xp << 16);
;             }
.LBB0_1478:
	s_or_b64 exec, exec, s[20:21]
	v_add_u32_e32 v20, 0x1000, v190
	s_mov_b32 s20, 0xf07fc3e1
	v_mul_hi_i32 v21, v20, s20
	v_add_u32_e32 v21, v21, v20
	v_lshrrev_b32_e32 v22, 31, v21
	v_ashrrev_i32_e32 v21, 10, v21
	v_add_u32_e32 v77, v21, v22
	v_mul_i32_i24_e32 v21, 0x442, v77
	v_sub_u32_e32 v60, v20, v21
	s_movk_i32 s20, 0x108
	v_cmp_gt_i32_e32 vcc, s20, v190
	v_subrev_u32_e32 v20, 28, v60
	s_movk_i32 s20, 0x402
	v_cmp_gt_u32_e64 s[20:21], s20, v20
	s_and_b64 s[70:71], vcc, s[20:21]
	v_mov_b32_e32 v23, 0
	v_lshlrev_b32_e32 v80, 4, v60
	v_mov_b32_e32 v22, 0
	v_mov_b32_e32 v21, 0
	v_mov_b32_e32 v20, 0
	v_mov_b32_e32 v81, 0
	s_and_saveexec_b64 s[66:67], s[70:71]
	s_cbranch_execz .LBB0_1484
	v_mov_b64_e32 v[20:21], s[48:49]
	s_mov_b32 s48, 0x1020000
	v_mad_i64_i32 v[20:21], s[48:49], v77, s48, v[20:21]
	v_mov_b32_e32 v81, v33
	v_lshl_add_u64 v[58:59], v[20:21], 0, v[80:81]
	global_load_dwordx4 v[20:23], v[58:59], off offset:-352
	v_cmp_lt_u32_e64 s[48:49], 28, v60
	v_mov_b32_e32 v81, 0
	v_mov_b32_e32 v61, 0
	s_and_saveexec_b64 s[70:71], s[48:49]
	s_cbranch_execz .LBB0_1481
	global_load_ushort v136, v[58:59], off offset:-354
.LBB0_1481:
	s_or_b64 exec, exec, s[70:71]
	s_movk_i32 s48, 0x41d
	v_cmp_gt_u32_e64 s[48:49], s48, v60
	s_and_saveexec_b64 s[70:71], s[48:49]
	s_cbranch_execz .LBB0_1483
	global_load_ushort v137, v[58:59], off offset:-336

; #define LAS __attribute__((address_space(3)))
; __device__ __forceinline__ unsigned cvtpk(float lo, float hi) { f32x2 v = {lo, hi}; bf16x2_t b = __builtin_convertvector(v, bf16x2_t); return __builtin_bit_cast(unsigned, b); }
; template <int NQ, int NB, int L>
; __device__ __forceinline__ void conv_unit(LAS unsigned char* lds, const Args& a, int j, int seq0, int c, int tid) {
;     ...
;                 const unsigned xm = p > 0 ? (unsigned)row[-1] : 0u, xp = (p + 8 < L) ? (unsigned)row[8] : 0u;
;                 halos[it] = xm | (xp << 16);
;     ...
;         for (int it = 0; it < NIT; ++it) {
;             const int idx = it * 512 + tid; const int b = idx / NCH, ch = idx % NCH, p = ch * 8 - PADL;
;             u32x4 o = {0u, 0u, 0u, 0u};
;             if (p >= 0 && p < L) {
;                 const u32x4 raw = raws[it];
;                 float x[10];
;                 x[0] = bflo(halos[it]); x[9] = bfhi(halos[it]);
;                 x[1] = bflo(raw.x); x[2] = bfhi(raw.x); x[3] = bflo(raw.y); x[4] = bfhi(raw.y); x[5] = bflo(raw.z); x[6] = bfhi(raw.z); x[7] = bflo(raw.w); x[8] = bfhi(raw.w);
;                 float y[8];
; #pragma unroll
;                 for (int i = 0; i < 8; ++i) y[i] = w0 * x[i] + w1 * x[i + 1] + w2 * x[i + 2] + bb;
;                 o.x = cvtpk(y[0], y[1]); o.y = cvtpk(y[2], y[3]); o.z = cvtpk(y[4], y[5]); o.w = cvtpk(y[6], y[7]);
;             }
;             if (idx < NB * NCH) *(LAS u32x4*)(lds + U_OFF + (b * LPD + ch * 8) * 2) = o;
.LBB0_1484:
	s_or_b64 exec, exec, s[66:67]
	s_waitcnt vmcnt(0)
	v_lshl_or_b32 v103, v121, 16, v120
	v_lshl_or_b32 v102, v123, 16, v122
	v_lshl_or_b32 v101, v125, 16, v124
	v_lshl_or_b32 v100, v127, 16, v126
	v_lshl_or_b32 v99, v129, 16, v128
	v_lshl_or_b32 v98, v131, 16, v130
	v_lshl_or_b32 v85, v133, 16, v132
	v_lshl_or_b32 v83, v135, 16, v134
	v_lshl_or_b32 v81, v137, 16, v136
	v_mov_b32_e32 v58, 0
	v_mov_b32_e32 v59, 0
	v_mov_b32_e32 v60, 0
	v_mov_b32_e32 v61, 0
	s_and_saveexec_b64 s[48:49], s[46:47]
	s_cbranch_execz .LBB0_1486
	v_and_b32_e32 v110, 0xffff0000, v28
	v_and_b32_e32 v109, 16, v30
	v_and_b32_e32 v108, 0xffff0000, v29
	v_lshlrev_b32_e32 v113, 16, v29
	v_mov_b32_e32 v112, v110
	v_and_b32_e32 v59, 16, v31
	v_and_b32_e32 v58, 0xffff0000, v30
	v_lshlrev_b32_e32 v61, 16, v31
	v_and_b32_e32 v104, 0xffff0000, v31
	v_lshlrev_b32_e32 v31, 16, v30
	v_mov_b32_e32 v30, v108
	v_pk_mov_b32 v[108:109], v[112:113], v[108:109] op_sel:[1,0]
	v_mov_b32_e32 v60, v58
	v_and_b32_e32 v105, 0xffff0000, v103
	v_and_b32_e32 v111, 16, v29
	v_lshlrev_b32_e32 v29, 16, v28
	v_lshlrev_b32_e32 v28, 16, v103
	s_waitcnt vmcnt(4)
	v_pk_mul_f32 v[108:109], v[74:75], v[108:109] op_sel_hi:[0,1]
	v_pk_mov_b32 v[58:59], v[30:31], v[58:59] op_sel:[1,0]
	v_pk_mov_b32 v[106:107], v[60:61], v[104:105] op_sel:[1,0]
	v_pk_mov_b32 v[110:111], v[28:29], v[110:111] op_sel:[1,0]
	s_waitcnt vmcnt(1)
	v_pk_fma_f32 v[108:109], v[76:77], v[112:113], v[108:109] op_sel_hi:[0,1,1]
	v_pk_mul_f32 v[58:59], v[74:75], v[58:59] op_sel_hi:[0,1]
	v_pk_mul_f32 v[110:111], v[74:75], v[110:111] op_sel_hi:[0,1]
	v_pk_fma_f32 v[108:109], v[72:73], v[30:31], v[108:109] op_sel_hi:[0,1,1]
	v_pk_fma_f32 v[30:31], v[76:77], v[30:31], v[58:59] op_sel_hi:[0,1,1]
	v_pk_mul_f32 v[58:59], v[74:75], v[106:107] op_sel_hi:[0,1]
	v_pk_fma_f32 v[28:29], v[76:77], v[28:29], v[110:111] op_sel_hi:[0,1,1]
	v_pk_fma_f32 v[58:59], v[76:77], v[60:61], v[58:59] op_sel_hi:[0,1,1]
	v_pk_fma_f32 v[28:29], v[72:73], v[112:113], v[28:29] op_sel_hi:[0,1,1]
	v_pk_fma_f32 v[30:31], v[72:73], v[60:61], v[30:31] op_sel_hi:[0,1,1]
	v_pk_fma_f32 v[58:59], v[72:73], v[104:105], v[58:59] op_sel_hi:[0,1,1]
	s_waitcnt vmcnt(0)
	v_pk_add_f32 v[28:29], v[78:79], v[28:29] op_sel_hi:[0,1]
	v_pk_add_f32 v[108:109], v[78:79], v[108:109] op_sel_hi:[0,1]
	v_pk_add_f32 v[30:31], v[78:79], v[30:31] op_sel_hi:[0,1]
	v_pk_add_f32 v[104:105], v[78:79], v[58:59] op_sel_hi:[0,1]
	v_cvt_pk_bf16_f32 v58, v28, v29
	v_cvt_pk_bf16_f32 v59, v108, v109
	v_cvt_pk_bf16_f32 v60, v30, v31
	v_cvt_pk_bf16_f32 v61, v104, v105
